# hyena ctx-item tap loop fully unrolled with 8-deep load prefetch (on top of fold fix)
# speedup vs baseline: 1.0084x; 1.0084x over previous
.LBB0_192:
	s_add_i32 s14, s2, 0xffffc000
	s_cmpk_lt_i32 s2, 0x4000
	s_cselect_b64 s[0:1], -1, 0
	s_and_b64 vcc, s[0:1], exec
	s_cselect_b32 s1, s3, 0
	s_cselect_b32 s0, s2, s14
	s_cselect_b32 s4, s79, s97
	s_cselect_b32 s5, s78, s96
	s_lshl_b64 s[0:1], s[0:1], 12
	s_add_u32 s0, s5, s0
	s_addc_u32 s1, s4, s1
	v_lshlrev_b32_e32 v56, 2, v34
	global_load_dwordx4 v[30:33], v56, s[0:1]
	global_load_dwordx4 v[26:29], v56, s[0:1] offset:1024
	global_load_dwordx4 v[22:25], v56, s[0:1] offset:2048
	global_load_dwordx4 v[18:21], v56, s[0:1] offset:3072
	s_cbranch_vccnz .LBB0_191
	s_lshl_b64 s[4:5], s[14:15], 12
	v_lshl_add_u64 v[42:43], v[36:37], 0, s[4:5]
	s_mov_b64 s[6:7], 0
	global_load_dwordx4 v[58:61], v[42:43], off
	global_load_dwordx4 v[62:65], v[42:43], off offset:1024
	global_load_dwordx4 v[66:69], v[42:43], off offset:2048
	global_load_dwordx4 v[70:73], v[42:43], off offset:3072
	s_add_u32 s6, s6, 0x200000
	v_lshl_add_u64 v[44:45], v[42:43], 0, s[6:7]
	global_load_dwordx4 v[74:77], v[44:45], off
	global_load_dwordx4 v[78:81], v[44:45], off offset:1024
	global_load_dwordx4 v[82:85], v[44:45], off offset:2048
	global_load_dwordx4 v[86:89], v[44:45], off offset:3072
	s_add_u32 s6, s6, 0x200000
	v_lshl_add_u64 v[44:45], v[42:43], 0, s[6:7]
	global_load_dwordx4 v[90:93], v[44:45], off
	global_load_dwordx4 v[94:97], v[44:45], off offset:1024
	global_load_dwordx4 v[98:101], v[44:45], off offset:2048
	global_load_dwordx4 v[102:105], v[44:45], off offset:3072
	s_add_u32 s6, s6, 0x200000
	v_lshl_add_u64 v[44:45], v[42:43], 0, s[6:7]
	global_load_dwordx4 v[106:109], v[44:45], off
	global_load_dwordx4 v[110:113], v[44:45], off offset:1024
	global_load_dwordx4 v[114:117], v[44:45], off offset:2048
	global_load_dwordx4 v[118:121], v[44:45], off offset:3072
	s_add_u32 s6, s6, 0x200000
	v_lshl_add_u64 v[44:45], v[42:43], 0, s[6:7]
	global_load_dwordx4 v[122:125], v[44:45], off
	global_load_dwordx4 v[126:129], v[44:45], off offset:1024
	global_load_dwordx4 v[130:133], v[44:45], off offset:2048
	global_load_dwordx4 v[134:137], v[44:45], off offset:3072
	s_add_u32 s6, s6, 0x200000
	v_lshl_add_u64 v[44:45], v[42:43], 0, s[6:7]
	global_load_dwordx4 v[138:141], v[44:45], off
	global_load_dwordx4 v[142:145], v[44:45], off offset:1024
	global_load_dwordx4 v[146:149], v[44:45], off offset:2048
	global_load_dwordx4 v[150:153], v[44:45], off offset:3072
	s_add_u32 s6, s6, 0x200000
	v_lshl_add_u64 v[44:45], v[42:43], 0, s[6:7]
	global_load_dwordx4 v[154:157], v[44:45], off
	global_load_dwordx4 v[158:161], v[44:45], off offset:1024
	global_load_dwordx4 v[162:165], v[44:45], off offset:2048
	global_load_dwordx4 v[166:169], v[44:45], off offset:3072
	s_add_u32 s6, s6, 0x200000
	v_lshl_add_u64 v[44:45], v[42:43], 0, s[6:7]
	global_load_dwordx4 v[170:173], v[44:45], off
	global_load_dwordx4 v[174:177], v[44:45], off offset:1024
	global_load_dwordx4 v[178:181], v[44:45], off offset:2048
	global_load_dwordx4 v[182:185], v[44:45], off offset:3072
	s_add_u32 s6, s6, 0x200000
	v_lshl_add_u64 v[44:45], v[42:43], 0, s[6:7]
	global_load_dwordx4 v[186:189], v[44:45], off
	global_load_dwordx4 v[190:193], v[44:45], off offset:1024
	global_load_dwordx4 v[194:197], v[44:45], off offset:2048
	global_load_dwordx4 v[214:217], v[44:45], off offset:3072
	s_add_u32 s6, s6, 0x200000
	v_lshl_add_u64 v[44:45], v[42:43], 0, s[6:7]
	global_load_dwordx4 v[218:221], v[44:45], off
	global_load_dwordx4 v[222:225], v[44:45], off offset:1024
	global_load_dwordx4 v[226:229], v[44:45], off offset:2048
	global_load_dwordx4 v[230:233], v[44:45], off offset:3072
	s_waitcnt vmcnt(39)
	v_pk_add_f32 v[32:33], v[32:33], v[60:61]
	v_pk_add_f32 v[30:31], v[30:31], v[58:59]
	s_add_u32 s6, s6, 0x200000
	v_lshl_add_u64 v[44:45], v[42:43], 0, s[6:7]
	global_load_dwordx4 v[58:61], v[44:45], off
	s_waitcnt vmcnt(39)
	v_pk_add_f32 v[28:29], v[28:29], v[64:65]
	v_pk_add_f32 v[26:27], v[26:27], v[62:63]
	global_load_dwordx4 v[62:65], v[44:45], off offset:1024
	s_waitcnt vmcnt(39)
	v_pk_add_f32 v[24:25], v[24:25], v[68:69]
	v_pk_add_f32 v[22:23], v[22:23], v[66:67]
	global_load_dwordx4 v[66:69], v[44:45], off offset:2048
	s_waitcnt vmcnt(39)
	v_pk_add_f32 v[20:21], v[20:21], v[72:73]
	v_pk_add_f32 v[18:19], v[18:19], v[70:71]
	global_load_dwordx4 v[70:73], v[44:45], off offset:3072
	s_waitcnt vmcnt(39)
	v_pk_add_f32 v[32:33], v[32:33], v[76:77]
	v_pk_add_f32 v[30:31], v[30:31], v[74:75]
	s_waitcnt vmcnt(38)
	v_pk_add_f32 v[28:29], v[28:29], v[80:81]
	v_pk_add_f32 v[26:27], v[26:27], v[78:79]
	s_waitcnt vmcnt(37)
	v_pk_add_f32 v[24:25], v[24:25], v[84:85]
	v_pk_add_f32 v[22:23], v[22:23], v[82:83]
	s_waitcnt vmcnt(36)
	v_pk_add_f32 v[20:21], v[20:21], v[88:89]
	v_pk_add_f32 v[18:19], v[18:19], v[86:87]
	s_waitcnt vmcnt(35)
	v_pk_add_f32 v[32:33], v[32:33], v[92:93]
	v_pk_add_f32 v[30:31], v[30:31], v[90:91]
	s_waitcnt vmcnt(34)
	v_pk_add_f32 v[28:29], v[28:29], v[96:97]
	v_pk_add_f32 v[26:27], v[26:27], v[94:95]
	s_waitcnt vmcnt(33)
	v_pk_add_f32 v[24:25], v[24:25], v[100:101]
	v_pk_add_f32 v[22:23], v[22:23], v[98:99]
	s_waitcnt vmcnt(32)
	v_pk_add_f32 v[20:21], v[20:21], v[104:105]
	v_pk_add_f32 v[18:19], v[18:19], v[102:103]
	s_waitcnt vmcnt(31)
	v_pk_add_f32 v[32:33], v[32:33], v[108:109]
	v_pk_add_f32 v[30:31], v[30:31], v[106:107]
	s_waitcnt vmcnt(30)
	v_pk_add_f32 v[28:29], v[28:29], v[112:113]
	v_pk_add_f32 v[26:27], v[26:27], v[110:111]
	s_waitcnt vmcnt(29)
	v_pk_add_f32 v[24:25], v[24:25], v[116:117]
	v_pk_add_f32 v[22:23], v[22:23], v[114:115]
	s_waitcnt vmcnt(28)
	v_pk_add_f32 v[20:21], v[20:21], v[120:121]
	v_pk_add_f32 v[18:19], v[18:19], v[118:119]
	s_waitcnt vmcnt(27)
	v_pk_add_f32 v[32:33], v[32:33], v[124:125]
	v_pk_add_f32 v[30:31], v[30:31], v[122:123]
	s_waitcnt vmcnt(26)
	v_pk_add_f32 v[28:29], v[28:29], v[128:129]
	v_pk_add_f32 v[26:27], v[26:27], v[126:127]
	s_waitcnt vmcnt(25)
	v_pk_add_f32 v[24:25], v[24:25], v[132:133]
	v_pk_add_f32 v[22:23], v[22:23], v[130:131]
	s_waitcnt vmcnt(24)
	v_pk_add_f32 v[20:21], v[20:21], v[136:137]
	v_pk_add_f32 v[18:19], v[18:19], v[134:135]
	s_waitcnt vmcnt(23)
	v_pk_add_f32 v[32:33], v[32:33], v[140:141]
	v_pk_add_f32 v[30:31], v[30:31], v[138:139]
	s_waitcnt vmcnt(22)
	v_pk_add_f32 v[28:29], v[28:29], v[144:145]
	v_pk_add_f32 v[26:27], v[26:27], v[142:143]
	s_waitcnt vmcnt(21)
	v_pk_add_f32 v[24:25], v[24:25], v[148:149]
	v_pk_add_f32 v[22:23], v[22:23], v[146:147]
	s_waitcnt vmcnt(20)
	v_pk_add_f32 v[20:21], v[20:21], v[152:153]
	v_pk_add_f32 v[18:19], v[18:19], v[150:151]
	s_waitcnt vmcnt(19)
	v_pk_add_f32 v[32:33], v[32:33], v[156:157]
	v_pk_add_f32 v[30:31], v[30:31], v[154:155]
	s_waitcnt vmcnt(18)
	v_pk_add_f32 v[28:29], v[28:29], v[160:161]
	v_pk_add_f32 v[26:27], v[26:27], v[158:159]
	s_waitcnt vmcnt(17)
	v_pk_add_f32 v[24:25], v[24:25], v[164:165]
	v_pk_add_f32 v[22:23], v[22:23], v[162:163]
	s_waitcnt vmcnt(16)
	v_pk_add_f32 v[20:21], v[20:21], v[168:169]
	v_pk_add_f32 v[18:19], v[18:19], v[166:167]
	s_waitcnt vmcnt(15)
	v_pk_add_f32 v[32:33], v[32:33], v[172:173]
	v_pk_add_f32 v[30:31], v[30:31], v[170:171]
	s_waitcnt vmcnt(14)
	v_pk_add_f32 v[28:29], v[28:29], v[176:177]
	v_pk_add_f32 v[26:27], v[26:27], v[174:175]
	s_waitcnt vmcnt(13)
	v_pk_add_f32 v[24:25], v[24:25], v[180:181]
	v_pk_add_f32 v[22:23], v[22:23], v[178:179]
	s_waitcnt vmcnt(12)
	v_pk_add_f32 v[20:21], v[20:21], v[184:185]
	v_pk_add_f32 v[18:19], v[18:19], v[182:183]
	s_waitcnt vmcnt(11)
	v_pk_add_f32 v[32:33], v[32:33], v[188:189]
	v_pk_add_f32 v[30:31], v[30:31], v[186:187]
	s_waitcnt vmcnt(10)
	v_pk_add_f32 v[28:29], v[28:29], v[192:193]
	v_pk_add_f32 v[26:27], v[26:27], v[190:191]
	s_waitcnt vmcnt(9)
	v_pk_add_f32 v[24:25], v[24:25], v[196:197]
	v_pk_add_f32 v[22:23], v[22:23], v[194:195]
	s_waitcnt vmcnt(8)
	v_pk_add_f32 v[20:21], v[20:21], v[216:217]
	v_pk_add_f32 v[18:19], v[18:19], v[214:215]
	s_waitcnt vmcnt(7)
	v_pk_add_f32 v[32:33], v[32:33], v[220:221]
	v_pk_add_f32 v[30:31], v[30:31], v[218:219]
	s_waitcnt vmcnt(6)
	v_pk_add_f32 v[28:29], v[28:29], v[224:225]
	v_pk_add_f32 v[26:27], v[26:27], v[222:223]
	s_waitcnt vmcnt(5)
	v_pk_add_f32 v[24:25], v[24:25], v[228:229]
	v_pk_add_f32 v[22:23], v[22:23], v[226:227]
	s_waitcnt vmcnt(4)
	v_pk_add_f32 v[20:21], v[20:21], v[232:233]
	v_pk_add_f32 v[18:19], v[18:19], v[230:231]
	s_waitcnt vmcnt(3)
	v_pk_add_f32 v[32:33], v[32:33], v[60:61]
	v_pk_add_f32 v[30:31], v[30:31], v[58:59]
	s_waitcnt vmcnt(2)
	v_pk_add_f32 v[28:29], v[28:29], v[64:65]
	v_pk_add_f32 v[26:27], v[26:27], v[62:63]
	s_waitcnt vmcnt(1)
	v_pk_add_f32 v[24:25], v[24:25], v[68:69]
	v_pk_add_f32 v[22:23], v[22:23], v[66:67]
	s_waitcnt vmcnt(0)
	v_pk_add_f32 v[20:21], v[20:21], v[72:73]
	v_pk_add_f32 v[18:19], v[18:19], v[70:71]
	v_lshl_add_u64 v[42:43], v[38:39], 0, s[4:5]
	global_store_dwordx4 v[42:43], v[30:33], off
	global_store_dwordx4 v[42:43], v[26:29], off offset:1024
	global_store_dwordx4 v[42:43], v[22:25], off offset:2048
	global_store_dwordx4 v[42:43], v[18:21], off offset:3072
	s_branch .LBB0_191

.LBB0_955:
	v_lshl_add_u64 v[10:11], s[92:93], 0, v[6:7]
	s_add_u32 s6, s92, s3
	v_add_co_u32_e32 v10, vcc, 0x1d140000, v10
	s_addc_u32 s7, s93, s4
	s_nop 0
	v_addc_co_u32_e32 v11, vcc, 0, v11, vcc
	v_mov_b32_e32 v12, 0x14f40000
	global_load_dwordx4 v[16:19], v[10:11], off offset:996
	global_load_dwordx4 v[20:23], v[10:11], off offset:1012
	global_load_dwordx4 v[24:27], v12, s[6:7]
	global_load_dwordx4 v[28:31], v[10:11], off offset:964
	global_load_dwordx4 v[32:35], v[10:11], off offset:980
	global_load_dwordx4 v[36:39], v12, s[6:7] offset:16
	global_load_dwordx4 v[40:43], v[10:11], off offset:932
	global_load_dwordx4 v[44:47], v[10:11], off offset:948
	global_load_dwordx4 v[48:51], v12, s[6:7] offset:32
	global_load_dwordx4 v[52:55], v[10:11], off offset:900
	global_load_dwordx4 v[56:59], v[10:11], off offset:916
	global_load_dwordx4 v[60:63], v12, s[6:7] offset:48
	global_load_dwordx4 v[64:67], v[10:11], off offset:868
	global_load_dwordx4 v[68:71], v[10:11], off offset:884
	global_load_dwordx4 v[72:75], v12, s[6:7] offset:64
	global_load_dwordx4 v[76:79], v[10:11], off offset:836
	global_load_dwordx4 v[80:83], v[10:11], off offset:852
	global_load_dwordx4 v[84:87], v12, s[6:7] offset:80
	global_load_dwordx4 v[88:91], v[10:11], off offset:804
	global_load_dwordx4 v[92:95], v[10:11], off offset:820
	global_load_dwordx4 v[96:99], v12, s[6:7] offset:96
	global_load_dwordx4 v[100:103], v[10:11], off offset:772
	global_load_dwordx4 v[104:107], v[10:11], off offset:788
	global_load_dwordx4 v[108:111], v12, s[6:7] offset:112
	s_waitcnt vmcnt(21)
	v_lshlrev_b32_e32 v112, 16, v24
	v_fmac_f32_e32 v9, v23, v112
	v_and_b32_e32 v113, 0xffff0000, v24
	v_fmac_f32_e32 v9, v22, v113
	v_lshlrev_b32_e32 v112, 16, v25
	v_fmac_f32_e32 v9, v21, v112
	v_and_b32_e32 v113, 0xffff0000, v25
	v_fmac_f32_e32 v9, v20, v113
	v_lshlrev_b32_e32 v112, 16, v26
	v_fmac_f32_e32 v9, v19, v112
	v_and_b32_e32 v113, 0xffff0000, v26
	v_fmac_f32_e32 v9, v18, v113
	v_lshlrev_b32_e32 v112, 16, v27
	v_fmac_f32_e32 v9, v17, v112
	v_and_b32_e32 v113, 0xffff0000, v27
	v_fmac_f32_e32 v9, v16, v113
	global_load_dwordx4 v[16:19], v[10:11], off offset:740
	global_load_dwordx4 v[20:23], v[10:11], off offset:756
	global_load_dwordx4 v[24:27], v12, s[6:7] offset:128
	s_waitcnt vmcnt(21)
	v_lshlrev_b32_e32 v112, 16, v36
	v_fmac_f32_e32 v9, v35, v112
	v_and_b32_e32 v113, 0xffff0000, v36
	v_fmac_f32_e32 v9, v34, v113
	v_lshlrev_b32_e32 v112, 16, v37
	v_fmac_f32_e32 v9, v33, v112
	v_and_b32_e32 v113, 0xffff0000, v37
	v_fmac_f32_e32 v9, v32, v113
	v_lshlrev_b32_e32 v112, 16, v38
	v_fmac_f32_e32 v9, v31, v112
	v_and_b32_e32 v113, 0xffff0000, v38
	v_fmac_f32_e32 v9, v30, v113
	v_lshlrev_b32_e32 v112, 16, v39
	v_fmac_f32_e32 v9, v29, v112
	v_and_b32_e32 v113, 0xffff0000, v39
	v_fmac_f32_e32 v9, v28, v113
	global_load_dwordx4 v[28:31], v[10:11], off offset:708
	global_load_dwordx4 v[32:35], v[10:11], off offset:724
	global_load_dwordx4 v[36:39], v12, s[6:7] offset:144
	s_waitcnt vmcnt(21)
	v_lshlrev_b32_e32 v112, 16, v48
	v_fmac_f32_e32 v9, v47, v112
	v_and_b32_e32 v113, 0xffff0000, v48
	v_fmac_f32_e32 v9, v46, v113
	v_lshlrev_b32_e32 v112, 16, v49
	v_fmac_f32_e32 v9, v45, v112
	v_and_b32_e32 v113, 0xffff0000, v49
	v_fmac_f32_e32 v9, v44, v113
	v_lshlrev_b32_e32 v112, 16, v50
	v_fmac_f32_e32 v9, v43, v112
	v_and_b32_e32 v113, 0xffff0000, v50
	v_fmac_f32_e32 v9, v42, v113
	v_lshlrev_b32_e32 v112, 16, v51
	v_fmac_f32_e32 v9, v41, v112
	v_and_b32_e32 v113, 0xffff0000, v51
	v_fmac_f32_e32 v9, v40, v113
	global_load_dwordx4 v[40:43], v[10:11], off offset:676
	global_load_dwordx4 v[44:47], v[10:11], off offset:692
	global_load_dwordx4 v[48:51], v12, s[6:7] offset:160
	s_waitcnt vmcnt(21)
	v_lshlrev_b32_e32 v112, 16, v60
	v_fmac_f32_e32 v9, v59, v112
	v_and_b32_e32 v113, 0xffff0000, v60
	v_fmac_f32_e32 v9, v58, v113
	v_lshlrev_b32_e32 v112, 16, v61
	v_fmac_f32_e32 v9, v57, v112
	v_and_b32_e32 v113, 0xffff0000, v61
	v_fmac_f32_e32 v9, v56, v113
	v_lshlrev_b32_e32 v112, 16, v62
	v_fmac_f32_e32 v9, v55, v112
	v_and_b32_e32 v113, 0xffff0000, v62
	v_fmac_f32_e32 v9, v54, v113
	v_lshlrev_b32_e32 v112, 16, v63
	v_fmac_f32_e32 v9, v53, v112
	v_and_b32_e32 v113, 0xffff0000, v63
	v_fmac_f32_e32 v9, v52, v113
	global_load_dwordx4 v[52:55], v[10:11], off offset:644
	global_load_dwordx4 v[56:59], v[10:11], off offset:660
	global_load_dwordx4 v[60:63], v12, s[6:7] offset:176
	s_waitcnt vmcnt(21)
	v_lshlrev_b32_e32 v112, 16, v72
	v_fmac_f32_e32 v9, v71, v112
	v_and_b32_e32 v113, 0xffff0000, v72
	v_fmac_f32_e32 v9, v70, v113
	v_lshlrev_b32_e32 v112, 16, v73
	v_fmac_f32_e32 v9, v69, v112
	v_and_b32_e32 v113, 0xffff0000, v73
	v_fmac_f32_e32 v9, v68, v113
	v_lshlrev_b32_e32 v112, 16, v74
	v_fmac_f32_e32 v9, v67, v112
	v_and_b32_e32 v113, 0xffff0000, v74
	v_fmac_f32_e32 v9, v66, v113
	v_lshlrev_b32_e32 v112, 16, v75
	v_fmac_f32_e32 v9, v65, v112
	v_and_b32_e32 v113, 0xffff0000, v75
	v_fmac_f32_e32 v9, v64, v113
	global_load_dwordx4 v[64:67], v[10:11], off offset:612
	global_load_dwordx4 v[68:71], v[10:11], off offset:628
	global_load_dwordx4 v[72:75], v12, s[6:7] offset:192
	s_waitcnt vmcnt(21)
	v_lshlrev_b32_e32 v112, 16, v84
	v_fmac_f32_e32 v9, v83, v112
	v_and_b32_e32 v113, 0xffff0000, v84
	v_fmac_f32_e32 v9, v82, v113
	v_lshlrev_b32_e32 v112, 16, v85
	v_fmac_f32_e32 v9, v81, v112
	v_and_b32_e32 v113, 0xffff0000, v85
	v_fmac_f32_e32 v9, v80, v113
	v_lshlrev_b32_e32 v112, 16, v86
	v_fmac_f32_e32 v9, v79, v112
	v_and_b32_e32 v113, 0xffff0000, v86
	v_fmac_f32_e32 v9, v78, v113
	v_lshlrev_b32_e32 v112, 16, v87
	v_fmac_f32_e32 v9, v77, v112
	v_and_b32_e32 v113, 0xffff0000, v87
	v_fmac_f32_e32 v9, v76, v113
	global_load_dwordx4 v[76:79], v[10:11], off offset:580
	global_load_dwordx4 v[80:83], v[10:11], off offset:596
	global_load_dwordx4 v[84:87], v12, s[6:7] offset:208
	s_waitcnt vmcnt(21)
	v_lshlrev_b32_e32 v112, 16, v96
	v_fmac_f32_e32 v9, v95, v112
	v_and_b32_e32 v113, 0xffff0000, v96
	v_fmac_f32_e32 v9, v94, v113
	v_lshlrev_b32_e32 v112, 16, v97
	v_fmac_f32_e32 v9, v93, v112
	v_and_b32_e32 v113, 0xffff0000, v97
	v_fmac_f32_e32 v9, v92, v113
	v_lshlrev_b32_e32 v112, 16, v98
	v_fmac_f32_e32 v9, v91, v112
	v_and_b32_e32 v113, 0xffff0000, v98
	v_fmac_f32_e32 v9, v90, v113
	v_lshlrev_b32_e32 v112, 16, v99
	v_fmac_f32_e32 v9, v89, v112
	v_and_b32_e32 v113, 0xffff0000, v99
	v_fmac_f32_e32 v9, v88, v113
	global_load_dwordx4 v[88:91], v[10:11], off offset:548
	global_load_dwordx4 v[92:95], v[10:11], off offset:564
	global_load_dwordx4 v[96:99], v12, s[6:7] offset:224
	s_waitcnt vmcnt(21)
	v_lshlrev_b32_e32 v112, 16, v108
	v_fmac_f32_e32 v9, v107, v112
	v_and_b32_e32 v113, 0xffff0000, v108
	v_fmac_f32_e32 v9, v106, v113
	v_lshlrev_b32_e32 v112, 16, v109
	v_fmac_f32_e32 v9, v105, v112
	v_and_b32_e32 v113, 0xffff0000, v109
	v_fmac_f32_e32 v9, v104, v113
	v_lshlrev_b32_e32 v112, 16, v110
	v_fmac_f32_e32 v9, v103, v112
	v_and_b32_e32 v113, 0xffff0000, v110
	v_fmac_f32_e32 v9, v102, v113
	v_lshlrev_b32_e32 v112, 16, v111
	v_fmac_f32_e32 v9, v101, v112
	v_and_b32_e32 v113, 0xffff0000, v111
	v_fmac_f32_e32 v9, v100, v113
	global_load_dwordx4 v[100:103], v[10:11], off offset:516
	global_load_dwordx4 v[104:107], v[10:11], off offset:532
	global_load_dwordx4 v[108:111], v12, s[6:7] offset:240
	s_waitcnt vmcnt(21)
	v_lshlrev_b32_e32 v112, 16, v24
	v_fmac_f32_e32 v9, v23, v112
	v_and_b32_e32 v113, 0xffff0000, v24
	v_fmac_f32_e32 v9, v22, v113
	v_lshlrev_b32_e32 v112, 16, v25
	v_fmac_f32_e32 v9, v21, v112
	v_and_b32_e32 v113, 0xffff0000, v25
	v_fmac_f32_e32 v9, v20, v113
	v_lshlrev_b32_e32 v112, 16, v26
	v_fmac_f32_e32 v9, v19, v112
	v_and_b32_e32 v113, 0xffff0000, v26
	v_fmac_f32_e32 v9, v18, v113
	v_lshlrev_b32_e32 v112, 16, v27
	v_fmac_f32_e32 v9, v17, v112
	v_and_b32_e32 v113, 0xffff0000, v27
	v_fmac_f32_e32 v9, v16, v113
	global_load_dwordx4 v[16:19], v[10:11], off offset:484
	global_load_dwordx4 v[20:23], v[10:11], off offset:500
	global_load_dwordx4 v[24:27], v12, s[6:7] offset:256
	s_waitcnt vmcnt(21)
	v_lshlrev_b32_e32 v112, 16, v36
	v_fmac_f32_e32 v9, v35, v112
	v_and_b32_e32 v113, 0xffff0000, v36
	v_fmac_f32_e32 v9, v34, v113
	v_lshlrev_b32_e32 v112, 16, v37
	v_fmac_f32_e32 v9, v33, v112
	v_and_b32_e32 v113, 0xffff0000, v37
	v_fmac_f32_e32 v9, v32, v113
	v_lshlrev_b32_e32 v112, 16, v38
	v_fmac_f32_e32 v9, v31, v112
	v_and_b32_e32 v113, 0xffff0000, v38
	v_fmac_f32_e32 v9, v30, v113
	v_lshlrev_b32_e32 v112, 16, v39
	v_fmac_f32_e32 v9, v29, v112
	v_and_b32_e32 v113, 0xffff0000, v39
	v_fmac_f32_e32 v9, v28, v113
	global_load_dwordx4 v[28:31], v[10:11], off offset:452
	global_load_dwordx4 v[32:35], v[10:11], off offset:468
	global_load_dwordx4 v[36:39], v12, s[6:7] offset:272
	s_waitcnt vmcnt(21)
	v_lshlrev_b32_e32 v112, 16, v48
	v_fmac_f32_e32 v9, v47, v112
	v_and_b32_e32 v113, 0xffff0000, v48
	v_fmac_f32_e32 v9, v46, v113
	v_lshlrev_b32_e32 v112, 16, v49
	v_fmac_f32_e32 v9, v45, v112
	v_and_b32_e32 v113, 0xffff0000, v49
	v_fmac_f32_e32 v9, v44, v113
	v_lshlrev_b32_e32 v112, 16, v50
	v_fmac_f32_e32 v9, v43, v112
	v_and_b32_e32 v113, 0xffff0000, v50
	v_fmac_f32_e32 v9, v42, v113
	v_lshlrev_b32_e32 v112, 16, v51
	v_fmac_f32_e32 v9, v41, v112
	v_and_b32_e32 v113, 0xffff0000, v51
	v_fmac_f32_e32 v9, v40, v113
	global_load_dwordx4 v[40:43], v[10:11], off offset:420
	global_load_dwordx4 v[44:47], v[10:11], off offset:436
	global_load_dwordx4 v[48:51], v12, s[6:7] offset:288
	s_waitcnt vmcnt(21)
	v_lshlrev_b32_e32 v112, 16, v60
	v_fmac_f32_e32 v9, v59, v112
	v_and_b32_e32 v113, 0xffff0000, v60
	v_fmac_f32_e32 v9, v58, v113
	v_lshlrev_b32_e32 v112, 16, v61
	v_fmac_f32_e32 v9, v57, v112
	v_and_b32_e32 v113, 0xffff0000, v61
	v_fmac_f32_e32 v9, v56, v113
	v_lshlrev_b32_e32 v112, 16, v62
	v_fmac_f32_e32 v9, v55, v112
	v_and_b32_e32 v113, 0xffff0000, v62
	v_fmac_f32_e32 v9, v54, v113
	v_lshlrev_b32_e32 v112, 16, v63
	v_fmac_f32_e32 v9, v53, v112
	v_and_b32_e32 v113, 0xffff0000, v63
	v_fmac_f32_e32 v9, v52, v113
	global_load_dwordx4 v[52:55], v[10:11], off offset:388
	global_load_dwordx4 v[56:59], v[10:11], off offset:404
	global_load_dwordx4 v[60:63], v12, s[6:7] offset:304
	s_waitcnt vmcnt(21)
	v_lshlrev_b32_e32 v112, 16, v72
	v_fmac_f32_e32 v9, v71, v112
	v_and_b32_e32 v113, 0xffff0000, v72
	v_fmac_f32_e32 v9, v70, v113
	v_lshlrev_b32_e32 v112, 16, v73
	v_fmac_f32_e32 v9, v69, v112
	v_and_b32_e32 v113, 0xffff0000, v73
	v_fmac_f32_e32 v9, v68, v113
	v_lshlrev_b32_e32 v112, 16, v74
	v_fmac_f32_e32 v9, v67, v112
	v_and_b32_e32 v113, 0xffff0000, v74
	v_fmac_f32_e32 v9, v66, v113
	v_lshlrev_b32_e32 v112, 16, v75
	v_fmac_f32_e32 v9, v65, v112
	v_and_b32_e32 v113, 0xffff0000, v75
	v_fmac_f32_e32 v9, v64, v113
	global_load_dwordx4 v[64:67], v[10:11], off offset:356
	global_load_dwordx4 v[68:71], v[10:11], off offset:372
	global_load_dwordx4 v[72:75], v12, s[6:7] offset:320
	s_waitcnt vmcnt(21)
	v_lshlrev_b32_e32 v112, 16, v84
	v_fmac_f32_e32 v9, v83, v112
	v_and_b32_e32 v113, 0xffff0000, v84
	v_fmac_f32_e32 v9, v82, v113
	v_lshlrev_b32_e32 v112, 16, v85
	v_fmac_f32_e32 v9, v81, v112
	v_and_b32_e32 v113, 0xffff0000, v85
	v_fmac_f32_e32 v9, v80, v113
	v_lshlrev_b32_e32 v112, 16, v86
	v_fmac_f32_e32 v9, v79, v112
	v_and_b32_e32 v113, 0xffff0000, v86
	v_fmac_f32_e32 v9, v78, v113
	v_lshlrev_b32_e32 v112, 16, v87
	v_fmac_f32_e32 v9, v77, v112
	v_and_b32_e32 v113, 0xffff0000, v87
	v_fmac_f32_e32 v9, v76, v113
	global_load_dwordx4 v[76:79], v[10:11], off offset:324
	global_load_dwordx4 v[80:83], v[10:11], off offset:340
	global_load_dwordx4 v[84:87], v12, s[6:7] offset:336
	s_waitcnt vmcnt(21)
	v_lshlrev_b32_e32 v112, 16, v96
	v_fmac_f32_e32 v9, v95, v112
	v_and_b32_e32 v113, 0xffff0000, v96
	v_fmac_f32_e32 v9, v94, v113
	v_lshlrev_b32_e32 v112, 16, v97
	v_fmac_f32_e32 v9, v93, v112
	v_and_b32_e32 v113, 0xffff0000, v97
	v_fmac_f32_e32 v9, v92, v113
	v_lshlrev_b32_e32 v112, 16, v98
	v_fmac_f32_e32 v9, v91, v112
	v_and_b32_e32 v113, 0xffff0000, v98
	v_fmac_f32_e32 v9, v90, v113
	v_lshlrev_b32_e32 v112, 16, v99
	v_fmac_f32_e32 v9, v89, v112
	v_and_b32_e32 v113, 0xffff0000, v99
	v_fmac_f32_e32 v9, v88, v113
	global_load_dwordx4 v[88:91], v[10:11], off offset:292
	global_load_dwordx4 v[92:95], v[10:11], off offset:308
	global_load_dwordx4 v[96:99], v12, s[6:7] offset:352
	s_waitcnt vmcnt(21)
	v_lshlrev_b32_e32 v112, 16, v108
	v_fmac_f32_e32 v9, v107, v112
	v_and_b32_e32 v113, 0xffff0000, v108
	v_fmac_f32_e32 v9, v106, v113
	v_lshlrev_b32_e32 v112, 16, v109
	v_fmac_f32_e32 v9, v105, v112
	v_and_b32_e32 v113, 0xffff0000, v109
	v_fmac_f32_e32 v9, v104, v113
	v_lshlrev_b32_e32 v112, 16, v110
	v_fmac_f32_e32 v9, v103, v112
	v_and_b32_e32 v113, 0xffff0000, v110
	v_fmac_f32_e32 v9, v102, v113
	v_lshlrev_b32_e32 v112, 16, v111
	v_fmac_f32_e32 v9, v101, v112
	v_and_b32_e32 v113, 0xffff0000, v111
	v_fmac_f32_e32 v9, v100, v113
	global_load_dwordx4 v[100:103], v[10:11], off offset:260
	global_load_dwordx4 v[104:107], v[10:11], off offset:276
	global_load_dwordx4 v[108:111], v12, s[6:7] offset:368
	s_waitcnt vmcnt(21)
	v_lshlrev_b32_e32 v112, 16, v24
	v_fmac_f32_e32 v9, v23, v112
	v_and_b32_e32 v113, 0xffff0000, v24
	v_fmac_f32_e32 v9, v22, v113
	v_lshlrev_b32_e32 v112, 16, v25
	v_fmac_f32_e32 v9, v21, v112
	v_and_b32_e32 v113, 0xffff0000, v25
	v_fmac_f32_e32 v9, v20, v113
	v_lshlrev_b32_e32 v112, 16, v26
	v_fmac_f32_e32 v9, v19, v112
	v_and_b32_e32 v113, 0xffff0000, v26
	v_fmac_f32_e32 v9, v18, v113
	v_lshlrev_b32_e32 v112, 16, v27
	v_fmac_f32_e32 v9, v17, v112
	v_and_b32_e32 v113, 0xffff0000, v27
	v_fmac_f32_e32 v9, v16, v113
	global_load_dwordx4 v[16:19], v[10:11], off offset:228
	global_load_dwordx4 v[20:23], v[10:11], off offset:244
	global_load_dwordx4 v[24:27], v12, s[6:7] offset:384
	s_waitcnt vmcnt(21)
	v_lshlrev_b32_e32 v112, 16, v36
	v_fmac_f32_e32 v9, v35, v112
	v_and_b32_e32 v113, 0xffff0000, v36
	v_fmac_f32_e32 v9, v34, v113
	v_lshlrev_b32_e32 v112, 16, v37
	v_fmac_f32_e32 v9, v33, v112
	v_and_b32_e32 v113, 0xffff0000, v37
	v_fmac_f32_e32 v9, v32, v113
	v_lshlrev_b32_e32 v112, 16, v38
	v_fmac_f32_e32 v9, v31, v112
	v_and_b32_e32 v113, 0xffff0000, v38
	v_fmac_f32_e32 v9, v30, v113
	v_lshlrev_b32_e32 v112, 16, v39
	v_fmac_f32_e32 v9, v29, v112
	v_and_b32_e32 v113, 0xffff0000, v39
	v_fmac_f32_e32 v9, v28, v113
	global_load_dwordx4 v[28:31], v[10:11], off offset:196
	global_load_dwordx4 v[32:35], v[10:11], off offset:212
	global_load_dwordx4 v[36:39], v12, s[6:7] offset:400
	s_waitcnt vmcnt(21)
	v_lshlrev_b32_e32 v112, 16, v48
	v_fmac_f32_e32 v9, v47, v112
	v_and_b32_e32 v113, 0xffff0000, v48
	v_fmac_f32_e32 v9, v46, v113
	v_lshlrev_b32_e32 v112, 16, v49
	v_fmac_f32_e32 v9, v45, v112
	v_and_b32_e32 v113, 0xffff0000, v49
	v_fmac_f32_e32 v9, v44, v113
	v_lshlrev_b32_e32 v112, 16, v50
	v_fmac_f32_e32 v9, v43, v112
	v_and_b32_e32 v113, 0xffff0000, v50
	v_fmac_f32_e32 v9, v42, v113
	v_lshlrev_b32_e32 v112, 16, v51
	v_fmac_f32_e32 v9, v41, v112
	v_and_b32_e32 v113, 0xffff0000, v51
	v_fmac_f32_e32 v9, v40, v113
	global_load_dwordx4 v[40:43], v[10:11], off offset:164
	global_load_dwordx4 v[44:47], v[10:11], off offset:180
	global_load_dwordx4 v[48:51], v12, s[6:7] offset:416
	s_waitcnt vmcnt(21)
	v_lshlrev_b32_e32 v112, 16, v60
	v_fmac_f32_e32 v9, v59, v112
	v_and_b32_e32 v113, 0xffff0000, v60
	v_fmac_f32_e32 v9, v58, v113
	v_lshlrev_b32_e32 v112, 16, v61
	v_fmac_f32_e32 v9, v57, v112
	v_and_b32_e32 v113, 0xffff0000, v61
	v_fmac_f32_e32 v9, v56, v113
	v_lshlrev_b32_e32 v112, 16, v62
	v_fmac_f32_e32 v9, v55, v112
	v_and_b32_e32 v113, 0xffff0000, v62
	v_fmac_f32_e32 v9, v54, v113
	v_lshlrev_b32_e32 v112, 16, v63
	v_fmac_f32_e32 v9, v53, v112
	v_and_b32_e32 v113, 0xffff0000, v63
	v_fmac_f32_e32 v9, v52, v113
	global_load_dwordx4 v[52:55], v[10:11], off offset:132
	global_load_dwordx4 v[56:59], v[10:11], off offset:148
	global_load_dwordx4 v[60:63], v12, s[6:7] offset:432
	s_waitcnt vmcnt(21)
	v_lshlrev_b32_e32 v112, 16, v72
	v_fmac_f32_e32 v9, v71, v112
	v_and_b32_e32 v113, 0xffff0000, v72
	v_fmac_f32_e32 v9, v70, v113
	v_lshlrev_b32_e32 v112, 16, v73
	v_fmac_f32_e32 v9, v69, v112
	v_and_b32_e32 v113, 0xffff0000, v73
	v_fmac_f32_e32 v9, v68, v113
	v_lshlrev_b32_e32 v112, 16, v74
	v_fmac_f32_e32 v9, v67, v112
	v_and_b32_e32 v113, 0xffff0000, v74
	v_fmac_f32_e32 v9, v66, v113
	v_lshlrev_b32_e32 v112, 16, v75
	v_fmac_f32_e32 v9, v65, v112
	v_and_b32_e32 v113, 0xffff0000, v75
	v_fmac_f32_e32 v9, v64, v113
	global_load_dwordx4 v[64:67], v[10:11], off offset:100
	global_load_dwordx4 v[68:71], v[10:11], off offset:116
	global_load_dwordx4 v[72:75], v12, s[6:7] offset:448
	s_waitcnt vmcnt(21)
	v_lshlrev_b32_e32 v112, 16, v84
	v_fmac_f32_e32 v9, v83, v112
	v_and_b32_e32 v113, 0xffff0000, v84
	v_fmac_f32_e32 v9, v82, v113
	v_lshlrev_b32_e32 v112, 16, v85
	v_fmac_f32_e32 v9, v81, v112
	v_and_b32_e32 v113, 0xffff0000, v85
	v_fmac_f32_e32 v9, v80, v113
	v_lshlrev_b32_e32 v112, 16, v86
	v_fmac_f32_e32 v9, v79, v112
	v_and_b32_e32 v113, 0xffff0000, v86
	v_fmac_f32_e32 v9, v78, v113
	v_lshlrev_b32_e32 v112, 16, v87
	v_fmac_f32_e32 v9, v77, v112
	v_and_b32_e32 v113, 0xffff0000, v87
	v_fmac_f32_e32 v9, v76, v113
	global_load_dwordx4 v[76:79], v[10:11], off offset:68
	global_load_dwordx4 v[80:83], v[10:11], off offset:84
	global_load_dwordx4 v[84:87], v12, s[6:7] offset:464
	s_waitcnt vmcnt(21)
	v_lshlrev_b32_e32 v112, 16, v96
	v_fmac_f32_e32 v9, v95, v112
	v_and_b32_e32 v113, 0xffff0000, v96
	v_fmac_f32_e32 v9, v94, v113
	v_lshlrev_b32_e32 v112, 16, v97
	v_fmac_f32_e32 v9, v93, v112
	v_and_b32_e32 v113, 0xffff0000, v97
	v_fmac_f32_e32 v9, v92, v113
	v_lshlrev_b32_e32 v112, 16, v98
	v_fmac_f32_e32 v9, v91, v112
	v_and_b32_e32 v113, 0xffff0000, v98
	v_fmac_f32_e32 v9, v90, v113
	v_lshlrev_b32_e32 v112, 16, v99
	v_fmac_f32_e32 v9, v89, v112
	v_and_b32_e32 v113, 0xffff0000, v99
	v_fmac_f32_e32 v9, v88, v113
	global_load_dwordx4 v[88:91], v[10:11], off offset:36
	global_load_dwordx4 v[92:95], v[10:11], off offset:52
	global_load_dwordx4 v[96:99], v12, s[6:7] offset:480
	s_waitcnt vmcnt(21)
	v_lshlrev_b32_e32 v112, 16, v108
	v_fmac_f32_e32 v9, v107, v112
	v_and_b32_e32 v113, 0xffff0000, v108
	v_fmac_f32_e32 v9, v106, v113
	v_lshlrev_b32_e32 v112, 16, v109
	v_fmac_f32_e32 v9, v105, v112
	v_and_b32_e32 v113, 0xffff0000, v109
	v_fmac_f32_e32 v9, v104, v113
	v_lshlrev_b32_e32 v112, 16, v110
	v_fmac_f32_e32 v9, v103, v112
	v_and_b32_e32 v113, 0xffff0000, v110
	v_fmac_f32_e32 v9, v102, v113
	v_lshlrev_b32_e32 v112, 16, v111
	v_fmac_f32_e32 v9, v101, v112
	v_and_b32_e32 v113, 0xffff0000, v111
	v_fmac_f32_e32 v9, v100, v113
	global_load_dwordx4 v[100:103], v[10:11], off offset:4
	global_load_dwordx4 v[104:107], v[10:11], off offset:20
	global_load_dwordx4 v[108:111], v12, s[6:7] offset:496
	s_waitcnt vmcnt(21)
	v_lshlrev_b32_e32 v112, 16, v24
	v_fmac_f32_e32 v9, v23, v112
	v_and_b32_e32 v113, 0xffff0000, v24
	v_fmac_f32_e32 v9, v22, v113
	v_lshlrev_b32_e32 v112, 16, v25
	v_fmac_f32_e32 v9, v21, v112
	v_and_b32_e32 v113, 0xffff0000, v25
	v_fmac_f32_e32 v9, v20, v113
	v_lshlrev_b32_e32 v112, 16, v26
	v_fmac_f32_e32 v9, v19, v112
	v_and_b32_e32 v113, 0xffff0000, v26
	v_fmac_f32_e32 v9, v18, v113
	v_lshlrev_b32_e32 v112, 16, v27
	v_fmac_f32_e32 v9, v17, v112
	v_and_b32_e32 v113, 0xffff0000, v27
	v_fmac_f32_e32 v9, v16, v113
	s_waitcnt vmcnt(18)
	v_lshlrev_b32_e32 v112, 16, v36
	v_fmac_f32_e32 v9, v35, v112
	v_and_b32_e32 v113, 0xffff0000, v36
	v_fmac_f32_e32 v9, v34, v113
	v_lshlrev_b32_e32 v112, 16, v37
	v_fmac_f32_e32 v9, v33, v112
	v_and_b32_e32 v113, 0xffff0000, v37
	v_fmac_f32_e32 v9, v32, v113
	v_lshlrev_b32_e32 v112, 16, v38
	v_fmac_f32_e32 v9, v31, v112
	v_and_b32_e32 v113, 0xffff0000, v38
	v_fmac_f32_e32 v9, v30, v113
	v_lshlrev_b32_e32 v112, 16, v39
	v_fmac_f32_e32 v9, v29, v112
	v_and_b32_e32 v113, 0xffff0000, v39
	v_fmac_f32_e32 v9, v28, v113
	s_waitcnt vmcnt(15)
	v_lshlrev_b32_e32 v112, 16, v48
	v_fmac_f32_e32 v9, v47, v112
	v_and_b32_e32 v113, 0xffff0000, v48
	v_fmac_f32_e32 v9, v46, v113
	v_lshlrev_b32_e32 v112, 16, v49
	v_fmac_f32_e32 v9, v45, v112
	v_and_b32_e32 v113, 0xffff0000, v49
	v_fmac_f32_e32 v9, v44, v113
	v_lshlrev_b32_e32 v112, 16, v50
	v_fmac_f32_e32 v9, v43, v112
	v_and_b32_e32 v113, 0xffff0000, v50
	v_fmac_f32_e32 v9, v42, v113
	v_lshlrev_b32_e32 v112, 16, v51
	v_fmac_f32_e32 v9, v41, v112
	v_and_b32_e32 v113, 0xffff0000, v51
	v_fmac_f32_e32 v9, v40, v113
	s_waitcnt vmcnt(12)
	v_lshlrev_b32_e32 v112, 16, v60
	v_fmac_f32_e32 v9, v59, v112
	v_and_b32_e32 v113, 0xffff0000, v60
	v_fmac_f32_e32 v9, v58, v113
	v_lshlrev_b32_e32 v112, 16, v61
	v_fmac_f32_e32 v9, v57, v112
	v_and_b32_e32 v113, 0xffff0000, v61
	v_fmac_f32_e32 v9, v56, v113
	v_lshlrev_b32_e32 v112, 16, v62
	v_fmac_f32_e32 v9, v55, v112
	v_and_b32_e32 v113, 0xffff0000, v62
	v_fmac_f32_e32 v9, v54, v113
	v_lshlrev_b32_e32 v112, 16, v63
	v_fmac_f32_e32 v9, v53, v112
	v_and_b32_e32 v113, 0xffff0000, v63
	v_fmac_f32_e32 v9, v52, v113
	s_waitcnt vmcnt(9)
	v_lshlrev_b32_e32 v112, 16, v72
	v_fmac_f32_e32 v9, v71, v112
	v_and_b32_e32 v113, 0xffff0000, v72
	v_fmac_f32_e32 v9, v70, v113
	v_lshlrev_b32_e32 v112, 16, v73
	v_fmac_f32_e32 v9, v69, v112
	v_and_b32_e32 v113, 0xffff0000, v73
	v_fmac_f32_e32 v9, v68, v113
	v_lshlrev_b32_e32 v112, 16, v74
	v_fmac_f32_e32 v9, v67, v112
	v_and_b32_e32 v113, 0xffff0000, v74
	v_fmac_f32_e32 v9, v66, v113
	v_lshlrev_b32_e32 v112, 16, v75
	v_fmac_f32_e32 v9, v65, v112
	v_and_b32_e32 v113, 0xffff0000, v75
	v_fmac_f32_e32 v9, v64, v113
	s_waitcnt vmcnt(6)
	v_lshlrev_b32_e32 v112, 16, v84
	v_fmac_f32_e32 v9, v83, v112
	v_and_b32_e32 v113, 0xffff0000, v84
	v_fmac_f32_e32 v9, v82, v113
	v_lshlrev_b32_e32 v112, 16, v85
	v_fmac_f32_e32 v9, v81, v112
	v_and_b32_e32 v113, 0xffff0000, v85
	v_fmac_f32_e32 v9, v80, v113
	v_lshlrev_b32_e32 v112, 16, v86
	v_fmac_f32_e32 v9, v79, v112
	v_and_b32_e32 v113, 0xffff0000, v86
	v_fmac_f32_e32 v9, v78, v113
	v_lshlrev_b32_e32 v112, 16, v87
	v_fmac_f32_e32 v9, v77, v112
	v_and_b32_e32 v113, 0xffff0000, v87
	v_fmac_f32_e32 v9, v76, v113
	s_waitcnt vmcnt(3)
	v_lshlrev_b32_e32 v112, 16, v96
	v_fmac_f32_e32 v9, v95, v112
	v_and_b32_e32 v113, 0xffff0000, v96
	v_fmac_f32_e32 v9, v94, v113
	v_lshlrev_b32_e32 v112, 16, v97
	v_fmac_f32_e32 v9, v93, v112
	v_and_b32_e32 v113, 0xffff0000, v97
	v_fmac_f32_e32 v9, v92, v113
	v_lshlrev_b32_e32 v112, 16, v98
	v_fmac_f32_e32 v9, v91, v112
	v_and_b32_e32 v113, 0xffff0000, v98
	v_fmac_f32_e32 v9, v90, v113
	v_lshlrev_b32_e32 v112, 16, v99
	v_fmac_f32_e32 v9, v89, v112
	v_and_b32_e32 v113, 0xffff0000, v99
	v_fmac_f32_e32 v9, v88, v113
	s_waitcnt vmcnt(0)
	v_lshlrev_b32_e32 v112, 16, v108
	v_fmac_f32_e32 v9, v107, v112
	v_and_b32_e32 v113, 0xffff0000, v108
	v_fmac_f32_e32 v9, v106, v113
	v_lshlrev_b32_e32 v112, 16, v109
	v_fmac_f32_e32 v9, v105, v112
	v_and_b32_e32 v113, 0xffff0000, v109
	v_fmac_f32_e32 v9, v104, v113
	v_lshlrev_b32_e32 v112, 16, v110
	v_fmac_f32_e32 v9, v103, v112
	v_and_b32_e32 v113, 0xffff0000, v110
	v_fmac_f32_e32 v9, v102, v113
	v_lshlrev_b32_e32 v112, 16, v111
	v_fmac_f32_e32 v9, v101, v112
	v_and_b32_e32 v113, 0xffff0000, v111
	v_fmac_f32_e32 v9, v100, v113
	s_and_b32 s4, s1, 0xff
	s_lshl_b32 s2, s2, 8
	s_or_b32 s5, s2, s4
	s_mul_i32 s2, s5, 0x4200
	s_mul_hi_i32 s3, s5, 0x4200
	s_add_u32 s2, s18, s2
	s_addc_u32 s3, s19, s3
	s_lshl_b32 s6, s4, 2
	global_load_ushort v11, v8, s[2:3]
	v_readlane_b32 s2, v254, 28
	v_mov_b32_e32 v10, s6
	v_readlane_b32 s3, v254, 29
	s_lshl_b32 s14, s4, 1
	s_add_i32 s0, s0, s8
	s_waitcnt vmcnt(0)
	v_lshlrev_b32_e32 v11, 16, v11
	s_nop 0
	global_load_dword v12, v10, s[2:3] offset:1024
	v_mad_i64_i32 v[6:7], s[2:3], s5, v213, v[2:3]
	v_readlane_b32 s2, v254, 37
	v_readlane_b32 s3, v254, 38
	global_load_ushort v13, v[6:7], off
	s_waitcnt vmcnt(1)
	v_div_scale_f32 v16, vcc, v9, v12, v9
	s_nop 1
	global_load_dword v10, v10, s[2:3]
	s_and_b32 s2, s1, 0xffffff00
	s_ashr_i32 s3, s2, 31
	v_lshl_add_u64 v[6:7], v[0:1], 0, s[2:3]
	v_readlane_b32 s2, v250, 15
	v_lshlrev_b64 v[6:7], 11, v[6:7]
	v_readlane_b32 s3, v250, 16
	s_waitcnt vmcnt(1)
	v_lshlrev_b32_e32 v13, 16, v13
	s_add_i32 s1, s1, s8
	v_lshl_add_u64 v[6:7], s[2:3], 0, v[6:7]
	v_div_scale_f32 v14, s[2:3], v12, v12, v9
	v_rcp_f32_e32 v15, v14
	s_movk_i32 s2, 0x7fff
	v_lshl_add_u64 v[6:7], v[6:7], 0, s[14:15]
	s_cmpk_lt_i32 s1, 0x200
	v_fma_f32 v17, -v14, v15, 1.0
	v_fmac_f32_e32 v15, v17, v15
	v_mul_f32_e32 v17, v16, v15
	v_fma_f32 v18, -v14, v17, v16
	v_fmac_f32_e32 v17, v18, v15
	v_fma_f32 v14, -v14, v17, v16
	v_div_fmas_f32 v14, v14, v15, v17
	v_div_fixup_f32 v9, v14, v12, v9
	s_waitcnt vmcnt(0)
	v_fmac_f32_e32 v9, v10, v11
	v_mul_f32_e32 v9, v9, v13
	v_bfe_u32 v10, v9, 16, 1
	v_add3_u32 v9, v9, v10, s2
	global_store_short_d16_hi v[6:7], v9, off offset:1024
	s_cbranch_scc1 .LBB0_954

.LBB0_1102:
	s_add_i32 s14, s6, 0xffffc000
	s_ashr_i32 s7, s6, 31
	s_cmpk_lt_i32 s6, 0x4000
	s_cselect_b64 s[8:9], -1, 0
	s_and_b64 s[10:11], s[8:9], exec
	s_cselect_b32 s11, s7, 0
	s_cselect_b32 s10, s6, s14
	s_cselect_b32 s5, s79, s97
	s_cselect_b32 s16, s78, s96
	s_lshl_b64 s[10:11], s[10:11], 12
	s_add_u32 s10, s16, s10
	s_addc_u32 s11, s5, s11
	global_load_dwordx4 v[30:33], v48, s[10:11]
	global_load_dwordx4 v[26:29], v48, s[10:11] offset:1024
	global_load_dwordx4 v[22:25], v48, s[10:11] offset:2048
	global_load_dwordx4 v[18:21], v48, s[10:11] offset:3072
	s_or_b64 s[8:9], s[2:3], s[8:9]
	s_and_b64 vcc, exec, s[8:9]
	s_cbranch_vccnz .LBB0_1101
	s_mov_b32 s5, s15
	s_lshl_b64 s[8:9], s[4:5], 12
	v_lshl_add_u64 v[40:41], v[38:39], 0, s[8:9]
	s_mov_b64 s[8:9], 0
	s_cmp_eq_u32 s13, 0x1600000
	s_cbranch_scc1 .Lfold_b11
	s_cmp_eq_u32 s13, 0x800000
	s_cbranch_scc1 .Lfold_b4
	s_branch .LBB0_1104
.Lfold_b11:
	v_add_co_u32_e32 v52, vcc, 0x1d340000, v40
	s_nop 1
	v_addc_co_u32_e32 v53, vcc, 0, v41, vcc
	s_mov_b64 s[8:9], 0
	global_load_dwordx4 v[56:59], v[52:53], off
	global_load_dwordx4 v[60:63], v[52:53], off offset:1024
	global_load_dwordx4 v[64:67], v[52:53], off offset:2048
	global_load_dwordx4 v[68:71], v[52:53], off offset:3072
	s_add_u32 s8, s8, 0x200000
	v_lshl_add_u64 v[54:55], v[52:53], 0, s[8:9]
	global_load_dwordx4 v[72:75], v[54:55], off
	global_load_dwordx4 v[76:79], v[54:55], off offset:1024
	global_load_dwordx4 v[80:83], v[54:55], off offset:2048
	global_load_dwordx4 v[84:87], v[54:55], off offset:3072
	s_add_u32 s8, s8, 0x200000
	v_lshl_add_u64 v[54:55], v[52:53], 0, s[8:9]
	global_load_dwordx4 v[88:91], v[54:55], off
	global_load_dwordx4 v[92:95], v[54:55], off offset:1024
	global_load_dwordx4 v[96:99], v[54:55], off offset:2048
	global_load_dwordx4 v[100:103], v[54:55], off offset:3072
	s_add_u32 s8, s8, 0x200000
	v_lshl_add_u64 v[54:55], v[52:53], 0, s[8:9]
	global_load_dwordx4 v[104:107], v[54:55], off
	global_load_dwordx4 v[108:111], v[54:55], off offset:1024
	global_load_dwordx4 v[112:115], v[54:55], off offset:2048
	global_load_dwordx4 v[116:119], v[54:55], off offset:3072
	s_add_u32 s8, s8, 0x200000
	v_lshl_add_u64 v[54:55], v[52:53], 0, s[8:9]
	global_load_dwordx4 v[120:123], v[54:55], off
	global_load_dwordx4 v[124:127], v[54:55], off offset:1024
	global_load_dwordx4 v[128:131], v[54:55], off offset:2048
	global_load_dwordx4 v[132:135], v[54:55], off offset:3072
	s_add_u32 s8, s8, 0x200000
	v_lshl_add_u64 v[54:55], v[52:53], 0, s[8:9]
	global_load_dwordx4 v[136:139], v[54:55], off
	global_load_dwordx4 v[140:143], v[54:55], off offset:1024
	global_load_dwordx4 v[144:147], v[54:55], off offset:2048
	global_load_dwordx4 v[148:151], v[54:55], off offset:3072
	s_add_u32 s8, s8, 0x200000
	v_lshl_add_u64 v[54:55], v[52:53], 0, s[8:9]
	global_load_dwordx4 v[152:155], v[54:55], off
	global_load_dwordx4 v[156:159], v[54:55], off offset:1024
	global_load_dwordx4 v[160:163], v[54:55], off offset:2048
	global_load_dwordx4 v[164:167], v[54:55], off offset:3072
	s_add_u32 s8, s8, 0x200000
	v_lshl_add_u64 v[54:55], v[52:53], 0, s[8:9]
	global_load_dwordx4 v[168:171], v[54:55], off
	global_load_dwordx4 v[172:175], v[54:55], off offset:1024
	global_load_dwordx4 v[176:179], v[54:55], off offset:2048
	global_load_dwordx4 v[180:183], v[54:55], off offset:3072
	s_add_u32 s8, s8, 0x200000
	v_lshl_add_u64 v[54:55], v[52:53], 0, s[8:9]
	global_load_dwordx4 v[184:187], v[54:55], off
	global_load_dwordx4 v[188:191], v[54:55], off offset:1024
	global_load_dwordx4 v[192:195], v[54:55], off offset:2048
	global_load_dwordx4 v[214:217], v[54:55], off offset:3072
	s_add_u32 s8, s8, 0x200000
	v_lshl_add_u64 v[54:55], v[52:53], 0, s[8:9]
	global_load_dwordx4 v[218:221], v[54:55], off
	global_load_dwordx4 v[222:225], v[54:55], off offset:1024
	global_load_dwordx4 v[226:229], v[54:55], off offset:2048
	global_load_dwordx4 v[230:233], v[54:55], off offset:3072
	s_waitcnt vmcnt(39)
	v_pk_add_f32 v[32:33], v[32:33], v[58:59]
	v_pk_add_f32 v[30:31], v[30:31], v[56:57]
	s_add_u32 s8, s8, 0x200000
	v_lshl_add_u64 v[54:55], v[52:53], 0, s[8:9]
	global_load_dwordx4 v[56:59], v[54:55], off
	s_waitcnt vmcnt(39)
	v_pk_add_f32 v[28:29], v[28:29], v[62:63]
	v_pk_add_f32 v[26:27], v[26:27], v[60:61]
	global_load_dwordx4 v[60:63], v[54:55], off offset:1024
	s_waitcnt vmcnt(39)
	v_pk_add_f32 v[24:25], v[24:25], v[66:67]
	v_pk_add_f32 v[22:23], v[22:23], v[64:65]
	global_load_dwordx4 v[64:67], v[54:55], off offset:2048
	s_waitcnt vmcnt(39)
	v_pk_add_f32 v[20:21], v[20:21], v[70:71]
	v_pk_add_f32 v[18:19], v[18:19], v[68:69]
	global_load_dwordx4 v[68:71], v[54:55], off offset:3072
	s_waitcnt vmcnt(39)
	v_pk_add_f32 v[32:33], v[32:33], v[74:75]
	v_pk_add_f32 v[30:31], v[30:31], v[72:73]
	s_waitcnt vmcnt(38)
	v_pk_add_f32 v[28:29], v[28:29], v[78:79]
	v_pk_add_f32 v[26:27], v[26:27], v[76:77]
	s_waitcnt vmcnt(37)
	v_pk_add_f32 v[24:25], v[24:25], v[82:83]
	v_pk_add_f32 v[22:23], v[22:23], v[80:81]
	s_waitcnt vmcnt(36)
	v_pk_add_f32 v[20:21], v[20:21], v[86:87]
	v_pk_add_f32 v[18:19], v[18:19], v[84:85]
	s_waitcnt vmcnt(35)
	v_pk_add_f32 v[32:33], v[32:33], v[90:91]
	v_pk_add_f32 v[30:31], v[30:31], v[88:89]
	s_waitcnt vmcnt(34)
	v_pk_add_f32 v[28:29], v[28:29], v[94:95]
	v_pk_add_f32 v[26:27], v[26:27], v[92:93]
	s_waitcnt vmcnt(33)
	v_pk_add_f32 v[24:25], v[24:25], v[98:99]
	v_pk_add_f32 v[22:23], v[22:23], v[96:97]
	s_waitcnt vmcnt(32)
	v_pk_add_f32 v[20:21], v[20:21], v[102:103]
	v_pk_add_f32 v[18:19], v[18:19], v[100:101]
	s_waitcnt vmcnt(31)
	v_pk_add_f32 v[32:33], v[32:33], v[106:107]
	v_pk_add_f32 v[30:31], v[30:31], v[104:105]
	s_waitcnt vmcnt(30)
	v_pk_add_f32 v[28:29], v[28:29], v[110:111]
	v_pk_add_f32 v[26:27], v[26:27], v[108:109]
	s_waitcnt vmcnt(29)
	v_pk_add_f32 v[24:25], v[24:25], v[114:115]
	v_pk_add_f32 v[22:23], v[22:23], v[112:113]
	s_waitcnt vmcnt(28)
	v_pk_add_f32 v[20:21], v[20:21], v[118:119]
	v_pk_add_f32 v[18:19], v[18:19], v[116:117]
	s_waitcnt vmcnt(27)
	v_pk_add_f32 v[32:33], v[32:33], v[122:123]
	v_pk_add_f32 v[30:31], v[30:31], v[120:121]
	s_waitcnt vmcnt(26)
	v_pk_add_f32 v[28:29], v[28:29], v[126:127]
	v_pk_add_f32 v[26:27], v[26:27], v[124:125]
	s_waitcnt vmcnt(25)
	v_pk_add_f32 v[24:25], v[24:25], v[130:131]
	v_pk_add_f32 v[22:23], v[22:23], v[128:129]
	s_waitcnt vmcnt(24)
	v_pk_add_f32 v[20:21], v[20:21], v[134:135]
	v_pk_add_f32 v[18:19], v[18:19], v[132:133]
	s_waitcnt vmcnt(23)
	v_pk_add_f32 v[32:33], v[32:33], v[138:139]
	v_pk_add_f32 v[30:31], v[30:31], v[136:137]
	s_waitcnt vmcnt(22)
	v_pk_add_f32 v[28:29], v[28:29], v[142:143]
	v_pk_add_f32 v[26:27], v[26:27], v[140:141]
	s_waitcnt vmcnt(21)
	v_pk_add_f32 v[24:25], v[24:25], v[146:147]
	v_pk_add_f32 v[22:23], v[22:23], v[144:145]
	s_waitcnt vmcnt(20)
	v_pk_add_f32 v[20:21], v[20:21], v[150:151]
	v_pk_add_f32 v[18:19], v[18:19], v[148:149]
	s_waitcnt vmcnt(19)
	v_pk_add_f32 v[32:33], v[32:33], v[154:155]
	v_pk_add_f32 v[30:31], v[30:31], v[152:153]
	s_waitcnt vmcnt(18)
	v_pk_add_f32 v[28:29], v[28:29], v[158:159]
	v_pk_add_f32 v[26:27], v[26:27], v[156:157]
	s_waitcnt vmcnt(17)
	v_pk_add_f32 v[24:25], v[24:25], v[162:163]
	v_pk_add_f32 v[22:23], v[22:23], v[160:161]
	s_waitcnt vmcnt(16)
	v_pk_add_f32 v[20:21], v[20:21], v[166:167]
	v_pk_add_f32 v[18:19], v[18:19], v[164:165]
	s_waitcnt vmcnt(15)
	v_pk_add_f32 v[32:33], v[32:33], v[170:171]
	v_pk_add_f32 v[30:31], v[30:31], v[168:169]
	s_waitcnt vmcnt(14)
	v_pk_add_f32 v[28:29], v[28:29], v[174:175]
	v_pk_add_f32 v[26:27], v[26:27], v[172:173]
	s_waitcnt vmcnt(13)
	v_pk_add_f32 v[24:25], v[24:25], v[178:179]
	v_pk_add_f32 v[22:23], v[22:23], v[176:177]
	s_waitcnt vmcnt(12)
	v_pk_add_f32 v[20:21], v[20:21], v[182:183]
	v_pk_add_f32 v[18:19], v[18:19], v[180:181]
	s_waitcnt vmcnt(11)
	v_pk_add_f32 v[32:33], v[32:33], v[186:187]
	v_pk_add_f32 v[30:31], v[30:31], v[184:185]
	s_waitcnt vmcnt(10)
	v_pk_add_f32 v[28:29], v[28:29], v[190:191]
	v_pk_add_f32 v[26:27], v[26:27], v[188:189]
	s_waitcnt vmcnt(9)
	v_pk_add_f32 v[24:25], v[24:25], v[194:195]
	v_pk_add_f32 v[22:23], v[22:23], v[192:193]
	s_waitcnt vmcnt(8)
	v_pk_add_f32 v[20:21], v[20:21], v[216:217]
	v_pk_add_f32 v[18:19], v[18:19], v[214:215]
	s_waitcnt vmcnt(7)
	v_pk_add_f32 v[32:33], v[32:33], v[220:221]
	v_pk_add_f32 v[30:31], v[30:31], v[218:219]
	s_waitcnt vmcnt(6)
	v_pk_add_f32 v[28:29], v[28:29], v[224:225]
	v_pk_add_f32 v[26:27], v[26:27], v[222:223]
	s_waitcnt vmcnt(5)
	v_pk_add_f32 v[24:25], v[24:25], v[228:229]
	v_pk_add_f32 v[22:23], v[22:23], v[226:227]
	s_waitcnt vmcnt(4)
	v_pk_add_f32 v[20:21], v[20:21], v[232:233]
	v_pk_add_f32 v[18:19], v[18:19], v[230:231]
	s_waitcnt vmcnt(3)
	v_pk_add_f32 v[32:33], v[32:33], v[58:59]
	v_pk_add_f32 v[30:31], v[30:31], v[56:57]
	s_waitcnt vmcnt(2)
	v_pk_add_f32 v[28:29], v[28:29], v[62:63]
	v_pk_add_f32 v[26:27], v[26:27], v[60:61]
	s_waitcnt vmcnt(1)
	v_pk_add_f32 v[24:25], v[24:25], v[66:67]
	v_pk_add_f32 v[22:23], v[22:23], v[64:65]
	s_waitcnt vmcnt(0)
	v_pk_add_f32 v[20:21], v[20:21], v[70:71]
	v_pk_add_f32 v[18:19], v[18:19], v[68:69]
	s_branch .Lfold_bdone
.Lfold_b4:
	v_add_co_u32_e32 v52, vcc, 0x1d340000, v40
	s_nop 1
	v_addc_co_u32_e32 v53, vcc, 0, v41, vcc
	s_mov_b64 s[8:9], 0
	global_load_dwordx4 v[56:59], v[52:53], off
	global_load_dwordx4 v[60:63], v[52:53], off offset:1024
	global_load_dwordx4 v[64:67], v[52:53], off offset:2048
	global_load_dwordx4 v[68:71], v[52:53], off offset:3072
	s_add_u32 s8, s8, 0x200000
	v_lshl_add_u64 v[54:55], v[52:53], 0, s[8:9]
	global_load_dwordx4 v[72:75], v[54:55], off
	global_load_dwordx4 v[76:79], v[54:55], off offset:1024
	global_load_dwordx4 v[80:83], v[54:55], off offset:2048
	global_load_dwordx4 v[84:87], v[54:55], off offset:3072
	s_add_u32 s8, s8, 0x200000
	v_lshl_add_u64 v[54:55], v[52:53], 0, s[8:9]
	global_load_dwordx4 v[88:91], v[54:55], off
	global_load_dwordx4 v[92:95], v[54:55], off offset:1024
	global_load_dwordx4 v[96:99], v[54:55], off offset:2048
	global_load_dwordx4 v[100:103], v[54:55], off offset:3072
	s_add_u32 s8, s8, 0x200000
	v_lshl_add_u64 v[54:55], v[52:53], 0, s[8:9]
	global_load_dwordx4 v[104:107], v[54:55], off
	global_load_dwordx4 v[108:111], v[54:55], off offset:1024
	global_load_dwordx4 v[112:115], v[54:55], off offset:2048
	global_load_dwordx4 v[116:119], v[54:55], off offset:3072
	s_waitcnt vmcnt(15)
	v_pk_add_f32 v[32:33], v[32:33], v[58:59]
	v_pk_add_f32 v[30:31], v[30:31], v[56:57]
	s_waitcnt vmcnt(14)
	v_pk_add_f32 v[28:29], v[28:29], v[62:63]
	v_pk_add_f32 v[26:27], v[26:27], v[60:61]
	s_waitcnt vmcnt(13)
	v_pk_add_f32 v[24:25], v[24:25], v[66:67]
	v_pk_add_f32 v[22:23], v[22:23], v[64:65]
	s_waitcnt vmcnt(12)
	v_pk_add_f32 v[20:21], v[20:21], v[70:71]
	v_pk_add_f32 v[18:19], v[18:19], v[68:69]
	s_waitcnt vmcnt(11)
	v_pk_add_f32 v[32:33], v[32:33], v[74:75]
	v_pk_add_f32 v[30:31], v[30:31], v[72:73]
	s_waitcnt vmcnt(10)
	v_pk_add_f32 v[28:29], v[28:29], v[78:79]
	v_pk_add_f32 v[26:27], v[26:27], v[76:77]
	s_waitcnt vmcnt(9)
	v_pk_add_f32 v[24:25], v[24:25], v[82:83]
	v_pk_add_f32 v[22:23], v[22:23], v[80:81]
	s_waitcnt vmcnt(8)
	v_pk_add_f32 v[20:21], v[20:21], v[86:87]
	v_pk_add_f32 v[18:19], v[18:19], v[84:85]
	s_waitcnt vmcnt(7)
	v_pk_add_f32 v[32:33], v[32:33], v[90:91]
	v_pk_add_f32 v[30:31], v[30:31], v[88:89]
	s_waitcnt vmcnt(6)
	v_pk_add_f32 v[28:29], v[28:29], v[94:95]
	v_pk_add_f32 v[26:27], v[26:27], v[92:93]
	s_waitcnt vmcnt(5)
	v_pk_add_f32 v[24:25], v[24:25], v[98:99]
	v_pk_add_f32 v[22:23], v[22:23], v[96:97]
	s_waitcnt vmcnt(4)
	v_pk_add_f32 v[20:21], v[20:21], v[102:103]
	v_pk_add_f32 v[18:19], v[18:19], v[100:101]
	s_waitcnt vmcnt(3)
	v_pk_add_f32 v[32:33], v[32:33], v[106:107]
	v_pk_add_f32 v[30:31], v[30:31], v[104:105]
	s_waitcnt vmcnt(2)
	v_pk_add_f32 v[28:29], v[28:29], v[110:111]
	v_pk_add_f32 v[26:27], v[26:27], v[108:109]
	s_waitcnt vmcnt(1)
	v_pk_add_f32 v[24:25], v[24:25], v[114:115]
	v_pk_add_f32 v[22:23], v[22:23], v[112:113]
	s_waitcnt vmcnt(0)
	v_pk_add_f32 v[20:21], v[20:21], v[118:119]
	v_pk_add_f32 v[18:19], v[18:19], v[116:117]
	s_branch .Lfold_bdone

.Lfold_bdone:
	s_lshl_b64 s[8:9], s[14:15], 12
	v_lshl_add_u64 v[40:41], v[34:35], 0, s[8:9]
	global_store_dwordx4 v[40:41], v[30:33], off
	global_store_dwordx4 v[40:41], v[26:29], off offset:1024
	global_store_dwordx4 v[40:41], v[22:25], off offset:2048
	global_store_dwordx4 v[40:41], v[18:21], off offset:3072
	s_branch .LBB0_1101
